# v46 + s_sleep removed from the per-step grid-barrier poll loop (tighter spin)
# speedup vs baseline: 1.0123x; 1.0061x over previous
; __device__ __forceinline__ unsigned xb_ld(unsigned* p)              { return __hip_atomic_load(p, __ATOMIC_RELAXED, __HIP_MEMORY_SCOPE_AGENT); }
; __device__ __forceinline__ unsigned xb_add(unsigned* p, unsigned v) { return __hip_atomic_fetch_add(p, v, __ATOMIC_RELAXED, __HIP_MEMORY_SCOPE_AGENT); }
; #define XB_SPIN(cond, bar) do { unsigned _sp = 0; while (cond) { __builtin_amdgcn_s_sleep(1); \
;     if ((++_sp & 255u) == 0u) { if (xb_ld(&(bar)[XB_TMO])) break; if (_sp > XB_SPIN_CAP) { atomicAdd(&(bar)[XB_TMO], 1u); break; } } } } while (0)
; __device__ __forceinline__ void xcd_barrier(const XcdBarrier& b) {
;     ...
;             else XB_SPIN(xb_ld(&bar[XB_TOPGEN]) == tg, bar);
;             __builtin_amdgcn_fence(__ATOMIC_ACQUIRE, "agent");
;             xb_add(&bar[XB_XGEN(b.x)], 1u);
;             asm volatile("s_waitcnt vmcnt(0)" ::: "memory");
;         } else {
;             XB_SPIN(xb_ld(&bar[XB_XGEN(b.x)]) == gen, bar);
.LBB0_545:
	s_and_b32 s7, s6, 0xff
	s_mov_b64 s[28:29], -1
	s_cmp_lg_u32 s7, 0
	s_mov_b64 s[38:39], -1
	s_cbranch_scc1 .LBB0_548
	global_load_dword v0, v157, s[16:17] sc1
	s_waitcnt vmcnt(0)
	v_cmp_eq_u32_e32 vcc, 0, v0
	s_cbranch_vccnz .LBB0_550
	s_mov_b64 s[38:39], 0
	s_mov_b64 s[36:37], -1
